# scan S4+S1 interval: s_setprio 3 for the critical waves 4,6,7 (solver and k/v step-vector waves)
# speedup vs baseline: 1.0144x; 1.0144x over previous
; __device__ __forceinline__ void scan_phase(PREF p, char* smem, const int wid_u) {
;     ...
;       lds_barrier();
;       if (wave == 4) {
.LBB0_548:
	s_waitcnt lgkmcnt(0)
	s_barrier
	s_cmp_lt_u32 s90, 4
	s_cbranch_scc1 .Lprio_i2_skip
	s_cmp_eq_u32 s90, 5
	s_cbranch_scc1 .Lprio_i2_skip
	s_setprio 3
.Lprio_i2_skip:
	s_mov_b64 s[82:83], -1
	s_mov_b64 s[40:41], 0
	s_cmp_lt_i32 s90, 5
	s_mov_b64 s[80:81], 0
	s_cbranch_scc0 .LBB0_552
	s_and_b64 vcc, exec, s[82:83]
	s_cbranch_vccnz .LBB0_555

; __device__ __forceinline__ void scan_phase(PREF p, char* smem, const int wid_u) {
;     ...
;       lds_barrier();
;       {
;         const int tt = wave & 1, rt = wave >> 1;
;         const f32x4 zero = {0.f, 0.f, 0.f, 0.f};
;         const bf16x8 tf = ldfrag(TT, 40, tt * 16, 0, fr, fq);
;         const f32x4 zacc = MFMA16(tf, ldfrag(VNb, 40, rt * 16, 0, fr, fq), zero);
;         const f32x4 wacc = MFMA16(tf, ldfrag(AtTb, 40, rt * 16, 0, fr, fq), zero);
;         *(uint2*)(Zb + (rt * 16 + fr) * 40 + tt * 16 + fq * 4) = pack4(zacc);
;         *(uint2*)(Wb + (rt * 16 + fr) * 40 + tt * 16 + fq * 4) = pack4(wacc);
;       }
;       lds_barrier();
;       f32x4 yacc = {0.f, 0.f, 0.f, 0.f};
;       {
;         const float pl0 = PLs[nt0 * 16 + fr], pl1 = PLs[nt1 * 16 + fr];
;         Sa = Sa * pl0; Sb = Sb * pl1;
;         const bf16x8 zf = ldfrag(Zb, 40, mt * 16, 0, fr, fq), vf = ldfrag(VT, 40, mt * 16, 0, fr, fq), wf = ldfrag(Wb, 40, mt * 16, 0, fr, fq);
;         const bf16x8 bb0 = ldfrag(Bb, 40, nt0 * 16, 0, fr, fq), bb1 = ldfrag(Bb, 40, nt1 * 16, 0, fr, fq);
;         const bf16x8 kb0 = ldfrag(Kb, 40, nt0 * 16, 0, fr, fq), kb1 = ldfrag(Kb, 40, nt1 * 16, 0, fr, fq);
;         const bf16x8 nbr = ldfrag(NbrT, 40, hn * 16, 0, fr, fq), nkr = ldfrag(NkrT, 40, hn * 16, 0, fr, fq);
;         Sa = MFMA16(zf, bb0, Sa); Sa = MFMA16(vf, kb0, Sa);
;         Sb = MFMA16(zf, bb1, Sb); Sb = MFMA16(vf, kb1, Sb);
;         yacc = MFMA16(zf, nbr, yacc); yacc = MFMA16(vf, nkr, yacc);
;         const f32x4 zero = {0.f, 0.f, 0.f, 0.f};
;         const f32x4 g0 = MFMA16(wf, bb0, zero), g1 = MFMA16(wf, bb1, zero);
;         f32x4 ry = MFMA16(wf, nbr, zero);
;         *(uint2*)(GT + (nt0 * 16 + fr) * 72 + mt * 16 + fq * 4) = pack4(g0);
;         *(uint2*)(GT + (nt1 * 16 + fr) * 72 + mt * 16 + fq * 4) = pack4(g1);
;         const uint2 rr = *(const uint2*)(Rt + (hn * 16 + fr) * 72 + mt * 16 + fq * 4);
;         ry[0] += bf_lo(rr.x); ry[1] += bf_hi(rr.x); ry[2] += bf_lo(rr.y); ry[3] += bf_hi(rr.y);
;         *(uint2*)(RyT + (hn * 16 + fr) * 72 + mt * 16 + fq * 4) = pack4(ry);
;       }
;       lds_barrier();
;       {
;         const bf16_t* Scur = Sbf + (c & 1) * 64 * 72;
;         bf16_t* Snext = Sbf + ((c + 1) & 1) * 64 * 72;
; #pragma unroll
;         for (int ks = 0; ks < 2; ++ks) {
;           const bf16x8 af = ldfrag(Scur, 72, mt * 16, ks * 32, fr, fq);
.LBB0_587:
	s_setprio 0
	s_waitcnt lgkmcnt(0)
	s_barrier
	ds_read_b128 v[56:59], v145 offset:13312
	ds_read_b128 v[60:63], v147 offset:39936
	ds_read_b128 v[64:67], v148
	s_and_b32 s40, s95, 64
	s_waitcnt lgkmcnt(1)
	v_mfma_f32_16x16x32_bf16 v[60:63], v[56:59], v[60:63], 0
	s_mulk_i32 s40, 0x90
	s_add_i32 s95, s95, 64
	s_andn2_b64 vcc, exec, s[80:81]
	s_waitcnt lgkmcnt(0)
	v_mfma_f32_16x16x32_bf16 v[56:59], v[56:59], v[64:67], 0
	s_nop 2
	v_cvt_pk_bf16_f32 v60, v60, v61
	v_cvt_pk_bf16_f32 v61, v62, v63
	s_nop 2
	v_cvt_pk_bf16_f32 v56, v56, v57
	v_cvt_pk_bf16_f32 v57, v58, v59
	ds_write2st64_b64 v149, v[56:57], v[60:61] offset0:31 offset1:41
	s_waitcnt lgkmcnt(0)
	s_barrier
	ds_read_b128 v[56:59], v147 offset:20992
	ds_read_b32 v78, v150
	ds_read_b128 v[60:63], v153
	ds_read_b128 v[64:67], v154
	ds_read_b32 v96, v151
	ds_read_b128 v[68:71], v152
	ds_read_b128 v[92:95], v147 offset:15872
	s_waitcnt lgkmcnt(5)
	v_pk_mul_f32 v[50:51], v[50:51], v[78:79] op_sel_hi:[1,0]
	v_pk_mul_f32 v[48:49], v[48:49], v[78:79] op_sel_hi:[1,0]
	s_waitcnt lgkmcnt(2)
	v_pk_mul_f32 v[54:55], v[54:55], v[96:97] op_sel_hi:[1,0]
	v_pk_mul_f32 v[52:53], v[52:53], v[96:97] op_sel_hi:[1,0]
	v_mfma_f32_16x16x32_bf16 v[48:51], v[56:59], v[60:63], v[48:51]
	ds_read_b128 v[96:99], v155
	ds_read_b128 v[100:103], v156
	v_add_u32_e32 v78, s40, v162
	s_and_b32 s40, s95, 64
	s_waitcnt lgkmcnt(2)
	v_mfma_f32_16x16x32_bf16 v[60:63], v[92:95], v[60:63], 0
	s_mulk_i32 s40, 0x90
	v_mfma_f32_16x16x32_bf16 v[52:55], v[56:59], v[64:67], v[52:55]
	v_mfma_f32_16x16x32_bf16 v[64:67], v[92:95], v[64:67], 0
	s_nop 4
	v_cvt_pk_bf16_f32 v60, v60, v61
	v_cvt_pk_bf16_f32 v61, v62, v63
	s_waitcnt lgkmcnt(1)
	v_mfma_f32_16x16x32_bf16 v[48:51], v[68:71], v[96:99], v[48:51]
	s_waitcnt lgkmcnt(0)
	v_mfma_f32_16x16x32_bf16 v[52:55], v[68:71], v[100:103], v[52:55]
	ds_read_b128 v[96:99], v145 offset:8192
	ds_read_b128 v[100:103], v145 offset:10752
	ds_write_b64 v158, v[60:61] offset:26112
	v_cvt_pk_bf16_f32 v60, v64, v65
	v_cvt_pk_bf16_f32 v61, v66, v67
	ds_write_b64 v160, v[60:61] offset:26112
	ds_read_b64 v[64:65], v161 offset:53760
	s_waitcnt lgkmcnt(4)
	v_mfma_f32_16x16x32_bf16 v[60:63], v[92:95], v[96:99], 0
	v_add_u32_e32 v92, v130, v157
	s_waitcnt lgkmcnt(0)
	v_lshlrev_b32_e32 v66, 16, v64
	v_and_b32_e32 v67, 0xffff0000, v64
	v_lshlrev_b32_e32 v64, 16, v65
	v_and_b32_e32 v65, 0xffff0000, v65
	s_nop 1
	v_pk_add_f32 v[60:61], v[60:61], v[66:67]
	v_pk_add_f32 v[62:63], v[62:63], v[64:65]
	v_cvt_pk_bf16_f32 v60, v60, v61
	v_cvt_pk_bf16_f32 v61, v62, v63
	ds_write_b64 v161, v[60:61] offset:35328
	s_waitcnt lgkmcnt(0)
	s_barrier
	ds_read_b128 v[60:63], v78
	v_mfma_f32_16x16x32_bf16 v[56:59], v[56:59], v[96:99], 0
	v_mfma_f32_16x16x32_bf16 v[56:59], v[68:71], v[100:103], v[56:59]
	ds_read_b128 v[64:67], v92 offset:26112
	ds_read_b128 v[68:71], v78 offset:64
	ds_read_b128 v[92:95], v92 offset:26176
	v_add_u32_e32 v78, v130, v159
	ds_read_b128 v[96:99], v78 offset:26176
	s_waitcnt lgkmcnt(3)
	v_mfma_f32_16x16x32_bf16 v[48:51], v[60:63], v[64:67], v[48:51]
	ds_read_b128 v[64:67], v78 offset:26112
	v_add_u32_e32 v100, v130, v128
	s_waitcnt lgkmcnt(0)
	v_mfma_f32_16x16x32_bf16 v[52:55], v[60:63], v[64:67], v[52:55]
	ds_read_b128 v[64:67], v100 offset:35328
	ds_read_b128 v[100:103], v100 offset:35392
	v_mfma_f32_16x16x32_bf16 v[48:51], v[68:71], v[92:95], v[48:51]
	v_mfma_f32_16x16x32_bf16 v[52:55], v[68:71], v[96:99], v[52:55]
	s_waitcnt lgkmcnt(1)
	v_mfma_f32_16x16x32_bf16 v[56:59], v[60:63], v[64:67], v[56:59]
	s_nop 4
	v_cvt_pk_bf16_f32 v60, v48, s0
	v_add_u32_e32 v61, s40, v168
	ds_write_b16 v61, v60
	v_cvt_pk_bf16_f32 v60, v52, s0
	ds_write_b16 v61, v60 offset:32
	v_cvt_pk_bf16_f32 v60, v49, s0
	ds_write_b16 v61, v60 offset:144
	v_cvt_pk_bf16_f32 v60, v53, s0
	s_waitcnt lgkmcnt(3)
	v_mfma_f32_16x16x32_bf16 v[56:59], v[68:71], v[100:103], v[56:59]
	ds_write_b16 v61, v60 offset:176
	v_cvt_pk_bf16_f32 v60, v50, s0
	ds_write_b16 v61, v60 offset:288
	v_cvt_pk_bf16_f32 v60, v54, s0
	ds_write_b16 v61, v60 offset:320
	v_cvt_pk_bf16_f32 v60, v51, s0
	ds_write_b16 v61, v60 offset:432
	v_cvt_pk_bf16_f32 v60, v55, s0
	ds_write_b16 v61, v60 offset:464
	s_cbranch_vccnz .LBB0_539
	ds_read_b32 v64, v81 offset:3840
	s_andn2_b64 vcc, exec, s[62:63]
	v_mov_b32_e32 v60, 1.0
	s_cbranch_vccnz .LBB0_590
	ds_read_b32 v60, v163
	s_waitcnt lgkmcnt(1)
	v_cndmask_b32_e64 v61, 1.0, v64, s[20:21]
	s_waitcnt lgkmcnt(0)
	v_mul_f32_e32 v60, v61, v60
